# DN chain step: 16 O stores converted to saddr form (per-lane offsets precomputed, per-step SGPR base) removing 64 VALU of address math per step
# baseline (speedup 1.0000x reference)
.LBB0_328:
	s_lshl_b32 s1, s0, 12
	s_lshl_b32 s13, s0, 8
	s_add_i32 s14, s1, 0xffff1000
	s_cmp_lt_i32 s0, 16
	s_cselect_b64 s[2:3], -1, 0
	s_and_b64 s[4:5], s[2:3], exec
	s_cselect_b32 s4, s13, s14
	s_cselect_b32 s1, 4, 64
	s_ashr_i32 s13, s4, 6
	s_cmp_eq_u32 s7, 0
	s_cselect_b64 s[68:69], -1, 0
	v_readlane_b32 s36, v246, 57
	s_and_b64 s[4:5], s[68:69], exec
	v_readlane_b32 s46, v245, 3
	v_readlane_b32 s47, v245, 4
	v_readlane_b32 s48, v245, 5
	v_readlane_b32 s49, v245, 6
	s_cselect_b32 s20, s47, s49
	s_cselect_b32 s21, s46, s48
	s_add_i32 s14, s1, -1
	s_and_b64 s[4:5], s[68:69], exec
	s_cselect_b32 s4, 0, s14
	s_add_i32 s4, s13, s4
	v_lshlrev_b32_e32 v53, 2, v51
	s_lshl_b32 s4, s4, 3
	s_lshl_b32 s5, s6, 1
	v_xor_b32_e32 v16, 63, v53
	s_or_b32 s4, s4, s5
	v_cndmask_b32_e64 v93, v16, v53, s[68:69]
	s_or_b32 s4, s4, s7
	v_lshlrev_b32_e32 v16, 3, v50
	s_ashr_i32 s5, s4, 31
	v_readlane_b32 s52, v246, 41
	v_ashrrev_i32_e32 v17, 31, v16
	s_lshl_b64 s[16:17], s[4:5], 13
	v_readlane_b32 s62, v246, 51
	v_lshlrev_b64 v[72:73], 1, v[16:17]
	v_add_u32_e32 v16, 0x800, v16
	v_readlane_b32 s63, v246, 52
	s_add_u32 s18, s62, s16
	v_ashrrev_i32_e32 v17, 31, v16
	v_readlane_b32 s64, v246, 53
	s_addc_u32 s19, s63, s17
	v_lshlrev_b64 v[74:75], 1, v[16:17]
	v_readlane_b32 s65, v246, 54
	v_lshl_add_u64 v[18:19], s[18:19], 0, v[72:73]
	s_waitcnt vmcnt(2)
	v_lshl_add_u64 v[20:21], s[18:19], 0, v[74:75]
	s_add_u32 s18, s64, s16
	v_readlane_b32 s66, v246, 55
	s_addc_u32 s19, s65, s17
	v_readlane_b32 s67, v246, 56
	v_lshl_add_u64 v[24:25], s[18:19], 0, v[72:73]
	v_lshl_add_u64 v[28:29], s[18:19], 0, v[74:75]
	s_add_u32 s18, s66, s16
	s_addc_u32 s19, s67, s17
	v_readlane_b32 s37, v246, 58
	v_lshl_add_u64 v[32:33], s[18:19], 0, v[72:73]
	v_lshl_add_u64 v[36:37], s[18:19], 0, v[74:75]
	s_add_u32 s18, s36, s16
	s_addc_u32 s19, s37, s17
	v_lshl_add_u64 v[40:41], s[18:19], 0, v[72:73]
	v_lshl_add_u64 v[44:45], s[18:19], 0, v[74:75]
	global_load_dwordx4 v[16:19], v[18:19], off
	s_nop 0
	global_load_dwordx4 v[20:23], v[20:21], off
	s_nop 0
	global_load_dwordx4 v[24:27], v[24:25], off
	s_nop 0
	global_load_dwordx4 v[28:31], v[28:29], off
	s_nop 0
	global_load_dwordx4 v[32:35], v[32:33], off
	s_nop 0
	global_load_dwordx4 v[36:39], v[36:37], off
	s_nop 0
	global_load_dwordx4 v[40:43], v[40:41], off
	s_nop 0
	global_load_dwordx4 v[44:47], v[44:45], off
	v_readlane_b32 s60, v246, 49
	v_readlane_b32 s61, v246, 50
	v_lshlrev_b32_e32 v48, 6, v68
	s_add_u32 s16, s60, s16
	v_readlane_b32 s38, v246, 59
	v_ashrrev_i32_e32 v49, 31, v48
	s_addc_u32 s17, s61, s17
	s_lshl_b64 s[4:5], s[4:5], 2
	v_readlane_b32 s39, v246, 60
	v_lshlrev_b64 v[54:55], 1, v[48:49]
	s_add_u32 s4, s38, s4
	v_lshlrev_b32_e32 v136, 3, v51
	v_lshl_add_u64 v[48:49], s[16:17], 0, v[54:55]
	s_addc_u32 s5, s39, s5
	v_lshl_add_u64 v[56:57], v[48:49], 0, v[136:137]
	global_load_dword v52, v137, s[4:5]
	global_load_dwordx2 v[48:49], v[56:57], off
	global_load_dwordx2 v[60:61], v[56:57], off offset:32
	global_load_dwordx2 v[90:91], v[56:57], off offset:64
	global_load_dwordx2 v[88:89], v[56:57], off offset:96
	v_and_b32_e32 v58, 15, v50
	v_lshrrev_b32_e32 v56, 3, v50
	v_lshlrev_b32_e32 v57, 4, v50
	v_add_u32_e32 v50, 0x100, v50
	s_movk_i32 s4, 0x90
	v_lshrrev_b32_e32 v50, 3, v50
	v_mul_lo_u32 v108, v56, s4
	v_and_b32_e32 v109, 0x70, v57
	v_mul_lo_u32 v111, v50, s4
	v_add_u32_e32 v57, v108, v109
	v_add_u32_e32 v50, v111, v109
	v_or_b32_e32 v107, 3, v53
	v_or_b32_e32 v106, 16, v53
	v_or_b32_e32 v105, 17, v53
	v_or_b32_e32 v104, 18, v53
	v_or_b32_e32 v103, 19, v53
	v_or_b32_e32 v102, 32, v53
	v_or_b32_e32 v100, 33, v53
	v_or_b32_e32 v98, 34, v53
	v_lshlrev_b32_e32 v51, 4, v51
	v_or_b32_e32 v97, 35, v53
	v_mad_u32_u24 v110, v58, s4, v51
	s_and_b32 s15, s26, 7
	s_lshl_b32 s4, s6, 7
	v_or_b32_e32 v96, 48, v53
	s_add_u32 s4, s21, s4
	s_waitcnt vmcnt(12)
	ds_write_b128 v57, v[16:19]
	s_waitcnt vmcnt(11)
	ds_write_b128 v50, v[20:23]
	s_waitcnt vmcnt(10)
	ds_write_b128 v57, v[24:27] offset:9216
	s_waitcnt vmcnt(9)
	ds_write_b128 v50, v[28:31] offset:9216
	s_waitcnt vmcnt(8)
	ds_write_b128 v57, v[32:35] offset:18432
	s_waitcnt vmcnt(7)
	ds_write_b128 v50, v[36:39] offset:18432
	s_waitcnt vmcnt(6)
	ds_write_b128 v57, v[40:43] offset:27648
	s_waitcnt vmcnt(5)
	ds_write_b128 v50, v[44:47] offset:27648
	v_xor_b32_e32 v50, 60, v53
	v_cndmask_b32_e64 v114, v50, v107, s[68:69]
	v_xor_b32_e32 v50, 47, v53
	v_cndmask_b32_e64 v115, v50, v106, s[68:69]
	v_xor_b32_e32 v50, 46, v53
	v_cndmask_b32_e64 v116, v50, v105, s[68:69]
	v_xor_b32_e32 v50, 45, v53
	v_cndmask_b32_e64 v117, v50, v104, s[68:69]
	v_xor_b32_e32 v50, 44, v53
	v_cndmask_b32_e64 v118, v50, v103, s[68:69]
	v_xor_b32_e32 v50, 31, v53
	v_cndmask_b32_e64 v119, v50, v102, s[68:69]
	v_xor_b32_e32 v50, 30, v53
	v_cndmask_b32_e64 v120, v50, v100, s[68:69]
	v_xor_b32_e32 v50, 29, v53
	v_cndmask_b32_e64 v121, v50, v98, s[68:69]
	v_xor_b32_e32 v50, 28, v53
	v_cndmask_b32_e64 v122, v50, v97, s[68:69]
	v_xor_b32_e32 v50, 15, v53
	v_cndmask_b32_e64 v123, v50, v96, s[68:69]
	v_or_b32_e32 v95, 49, v53
	v_xor_b32_e32 v50, 14, v53
	v_ashrrev_i32_e32 v69, 31, v68
	s_addc_u32 s5, s20, 0
	v_cndmask_b32_e64 v124, v50, v95, s[68:69]
	v_or_b32_e32 v94, 50, v53
	v_xor_b32_e32 v50, 13, v53
	v_or_b32_e32 v101, 1, v53
	v_xor_b32_e32 v51, 62, v53
	v_lshl_add_u64 v[76:77], v[68:69], 1, s[4:5]
	v_cndmask_b32_e64 v125, v50, v94, s[68:69]
	v_or_b32_e32 v69, 51, v53
	v_xor_b32_e32 v50, 12, v53
	v_or_b32_e32 v99, 2, v53
	v_xor_b32_e32 v56, 61, v53
	v_cndmask_b32_e64 v112, v51, v101, s[68:69]
	v_cndmask_b32_e64 v126, v50, v69, s[68:69]
	v_lshl_add_u64 v[50:51], s[60:61], 0, v[54:55]
	s_mov_b32 s18, 0
	v_cndmask_b32_e64 v113, v56, v99, s[68:69]
	v_lshl_add_u64 v[78:79], v[50:51], 0, v[136:137]
	s_waitcnt vmcnt(4)
	v_mov_b32_e32 v127, v52
	s_waitcnt vmcnt(3)
	v_mov_b64_e32 v[80:81], v[48:49]
	s_waitcnt vmcnt(2)
	v_mov_b64_e32 v[82:83], v[60:61]
	s_waitcnt vmcnt(1)
	v_mov_b64_e32 v[84:85], v[90:91]
	s_waitcnt vmcnt(0)
	v_mov_b64_e32 v[86:87], v[88:89]
	s_movk_i32 s36, 0x880
	v_readlane_b32 s40, v246, 61
	v_readlane_b32 s41, v246, 62
	v_readlane_b32 s42, v246, 63
	v_readlane_b32 s43, v245, 0
	v_readlane_b32 s44, v245, 1
	v_readlane_b32 s45, v245, 2
	v_readlane_b32 s50, v245, 7
	v_readlane_b32 s51, v245, 8
	v_readlane_b32 s53, v246, 42
	v_readlane_b32 s54, v246, 43
	v_readlane_b32 s55, v246, 44
	v_readlane_b32 s56, v246, 45
	v_readlane_b32 s57, v246, 46
	v_readlane_b32 s58, v246, 47
	v_readlane_b32 s59, v246, 48
	s_waitcnt lgkmcnt(0)
	s_barrier
	v_and_b32_e32 v202, 15, v68
	v_lshlrev_b32_e32 v202, 1, v202
	v_lshl_add_u32 v93, v93, 9, v202
	v_lshl_add_u32 v112, v112, 9, v202
	v_lshl_add_u32 v113, v113, 9, v202
	v_lshl_add_u32 v114, v114, 9, v202
	v_lshl_add_u32 v115, v115, 9, v202
	v_lshl_add_u32 v116, v116, 9, v202
	v_lshl_add_u32 v117, v117, 9, v202
	v_lshl_add_u32 v118, v118, 9, v202
	v_lshl_add_u32 v119, v119, 9, v202
	v_lshl_add_u32 v120, v120, 9, v202
	v_lshl_add_u32 v121, v121, 9, v202
	v_lshl_add_u32 v122, v122, 9, v202
	v_lshl_add_u32 v123, v123, 9, v202
	v_lshl_add_u32 v124, v124, 9, v202
	v_lshl_add_u32 v125, v125, 9, v202
	v_lshl_add_u32 v126, v126, 9, v202
	v_readfirstlane_b32 s98, v76
	v_readfirstlane_b32 s99, v77
	s_branch .LBB0_330

.LBB0_332:
	v_mul_f32_e32 v50, 0x3fb8aa3b, v52
	s_and_b64 s[20:21], s[68:69], exec
	v_exp_f32_e32 v92, v50
	s_cselect_b32 s17, s18, s14
	s_bitcmp1_b32 s18, 0
	s_cselect_b32 s18, 0x9000, 0
	v_add_u32_e32 v128, s18, v110
	ds_read_b128 v[56:59], v128
	ds_read_b128 v[130:133], v128 offset:9216
	v_cvt_pk_bf16_f32 v64, v12, v13
	v_cvt_pk_bf16_f32 v65, v14, v15
	v_cvt_pk_bf16_f32 v66, v0, v1
	v_cvt_pk_bf16_f32 v67, v2, v3
	ds_read_b128 v[146:149], v128 offset:64
	ds_read_b128 v[150:153], v128 offset:9280
	s_waitcnt lgkmcnt(3)
	v_mfma_f32_16x16x32_bf16 v[56:59], v[56:59], v[64:67], 0
	v_cvt_pk_bf16_f32 v52, v8, v9
	v_cvt_pk_bf16_f32 v53, v10, v11
	v_cvt_pk_bf16_f32 v54, v4, v5
	v_cvt_pk_bf16_f32 v55, v6, v7
	s_waitcnt lgkmcnt(2)
	v_mfma_f32_16x16x32_bf16 v[130:133], v[130:133], v[64:67], 0
	v_lshlrev_b32_e32 v50, 16, v48
	v_and_b32_e32 v51, 0xffff0000, v48
	v_lshlrev_b32_e32 v48, 16, v49
	s_waitcnt lgkmcnt(1)
	v_mfma_f32_16x16x32_bf16 v[146:149], v[146:149], v[52:55], v[56:59]
	v_and_b32_e32 v49, 0xffff0000, v49
	v_lshlrev_b32_e32 v62, 16, v60
	v_and_b32_e32 v63, 0xffff0000, v60
	s_waitcnt lgkmcnt(0)
	v_mfma_f32_16x16x32_bf16 v[56:59], v[150:153], v[52:55], v[130:133]
	v_lshlrev_b32_e32 v60, 16, v61
	s_nop 1
	v_pk_add_f32 v[134:135], v[50:51], v[146:147] neg_lo:[0,1] neg_hi:[0,1]
	v_pk_add_f32 v[154:155], v[48:49], v[148:149] neg_lo:[0,1] neg_hi:[0,1]
	ds_read_b128 v[48:51], v128 offset:2304
	ds_read_b128 v[130:133], v128 offset:11520
	s_waitcnt lgkmcnt(1)
	v_mfma_f32_16x16x32_bf16 v[48:51], v[48:51], v[64:67], 0
	ds_read_b128 v[146:149], v128 offset:2368
	ds_read_b128 v[150:153], v128 offset:11584
	v_and_b32_e32 v61, 0xffff0000, v61
	v_pk_mul_f32 v[12:13], v[12:13], v[92:93] op_sel_hi:[1,0]
	s_waitcnt lgkmcnt(2)
	v_mfma_f32_16x16x32_bf16 v[130:133], v[130:133], v[64:67], 0
	v_mul_f32_e64 v14, v14, v92
	v_mul_f32_e64 v15, v15, v92
	v_pk_mul_f32 v[0:1], v[0:1], v[92:93] op_sel_hi:[1,0]
	v_pk_mul_f32 v[2:3], v[2:3], v[92:93] op_sel_hi:[1,0]
	s_waitcnt lgkmcnt(1)
	v_mfma_f32_16x16x32_bf16 v[146:149], v[146:149], v[52:55], v[48:51]
	v_mul_f32_e64 v8, v8, v92
	v_mul_f32_e64 v9, v9, v92
	v_pk_mul_f32 v[10:11], v[10:11], v[92:93] op_sel_hi:[1,0]
	v_pk_mul_f32 v[4:5], v[4:5], v[92:93] op_sel_hi:[1,0]
	s_waitcnt lgkmcnt(0)
	v_mfma_f32_16x16x32_bf16 v[48:51], v[150:153], v[52:55], v[130:133]
	v_mul_f32_e64 v6, v6, v92
	v_mul_f32_e64 v7, v7, v92
	v_pk_add_f32 v[156:157], v[62:63], v[146:147] neg_lo:[0,1] neg_hi:[0,1]
	v_pk_add_f32 v[158:159], v[60:61], v[148:149] neg_lo:[0,1] neg_hi:[0,1]
	ds_read_b128 v[60:63], v128 offset:4608
	ds_read_b128 v[130:133], v128 offset:13824
	s_waitcnt lgkmcnt(1)
	v_mfma_f32_16x16x32_bf16 v[60:63], v[60:63], v[64:67], 0
	ds_read_b128 v[146:149], v128 offset:4672
	ds_read_b128 v[150:153], v128 offset:13888
	s_add_i32 s17, s17, s13
	s_lshl_b32 s17, s17, 6
	s_lshl_b32 s20, s17, 9
	s_add_u32 s20, s98, s20
	s_addc_u32 s21, s99, 0
	s_waitcnt lgkmcnt(2)
	v_mfma_f32_16x16x32_bf16 v[130:133], v[130:133], v[64:67], 0
	s_waitcnt lgkmcnt(1)
	v_mfma_f32_16x16x32_bf16 v[146:149], v[146:149], v[52:55], v[60:63]
	s_waitcnt lgkmcnt(0)
	v_mfma_f32_16x16x32_bf16 v[60:63], v[150:153], v[52:55], v[130:133]
	s_nop 3
	v_lshlrev_b32_e32 v130, 16, v90
	v_and_b32_e32 v131, 0xffff0000, v90
	v_lshlrev_b32_e32 v90, 16, v91
	v_and_b32_e32 v91, 0xffff0000, v91
	v_pk_add_f32 v[160:161], v[130:131], v[146:147] neg_lo:[0,1] neg_hi:[0,1]
	v_pk_add_f32 v[90:91], v[90:91], v[148:149] neg_lo:[0,1] neg_hi:[0,1]
	ds_read_b128 v[130:133], v128 offset:6912
	ds_read_b128 v[146:149], v128 offset:16128
	s_waitcnt lgkmcnt(1)
	v_mfma_f32_16x16x32_bf16 v[130:133], v[130:133], v[64:67], 0
	s_waitcnt lgkmcnt(0)
	v_mfma_f32_16x16x32_bf16 v[64:67], v[146:149], v[64:67], 0
	ds_read_b128 v[146:149], v128 offset:6976
	ds_read_b128 v[150:153], v128 offset:16192
	s_waitcnt lgkmcnt(1)
	v_mfma_f32_16x16x32_bf16 v[130:133], v[146:149], v[52:55], v[130:133]
	s_waitcnt lgkmcnt(0)
	v_mfma_f32_16x16x32_bf16 v[52:55], v[150:153], v[52:55], v[64:67]
	s_nop 2
	v_lshlrev_b32_e32 v64, 16, v88
	v_and_b32_e32 v65, 0xffff0000, v88
	s_nop 0
	v_pk_add_f32 v[130:131], v[64:65], v[130:131] neg_lo:[0,1] neg_hi:[0,1]
	v_lshlrev_b32_e32 v64, 16, v89
	v_and_b32_e32 v65, 0xffff0000, v89
	v_pk_add_f32 v[132:133], v[64:65], v[132:133] neg_lo:[0,1] neg_hi:[0,1]
	v_cvt_pk_bf16_f32 v89, v90, v91
	v_cvt_pk_bf16_f32 v90, v130, v131
	v_cvt_pk_bf16_f32 v91, v132, v133
	ds_read_b128 v[130:133], v128 offset:18432
	ds_read_b128 v[146:149], v128 offset:27648
	v_cvt_pk_bf16_f32 v64, v134, v135
	v_cvt_pk_bf16_f32 v65, v154, v155
	v_cvt_pk_bf16_f32 v66, v156, v157
	v_cvt_pk_bf16_f32 v67, v158, v159
	v_cvt_pk_bf16_f32 v88, v160, v161
	s_waitcnt lgkmcnt(1)
	v_mfma_f32_16x16x32_bf16 v[56:59], v[130:133], v[64:67], v[56:59]
	s_waitcnt lgkmcnt(0)
	v_mfma_f32_16x16x32_bf16 v[12:15], v[146:149], v[64:67], v[12:15]
	ds_read_b128 v[130:133], v128 offset:18496
	ds_read_b128 v[146:149], v128 offset:27712
	s_waitcnt lgkmcnt(1)
	v_mfma_f32_16x16x32_bf16 v[56:59], v[130:133], v[88:91], v[56:59]
	s_waitcnt lgkmcnt(0)
	v_mfma_f32_16x16x32_bf16 v[12:15], v[146:149], v[88:91], v[12:15]
	ds_read_b128 v[130:133], v128 offset:20736
	ds_read_b128 v[146:149], v128 offset:29952
	s_nop 3
	v_cvt_pk_bf16_f32 v56, v56, s0
	v_cvt_pk_bf16_f32 v58, v58, s0
	s_waitcnt lgkmcnt(1)
	v_mfma_f32_16x16x32_bf16 v[48:51], v[130:133], v[64:67], v[48:51]
	s_waitcnt lgkmcnt(0)
	v_mfma_f32_16x16x32_bf16 v[0:3], v[146:149], v[64:67], v[0:3]
	ds_read_b128 v[130:133], v128 offset:20800
	ds_read_b128 v[146:149], v128 offset:30016
	s_waitcnt lgkmcnt(1)
	v_mfma_f32_16x16x32_bf16 v[48:51], v[130:133], v[88:91], v[48:51]
	s_waitcnt lgkmcnt(0)
	v_mfma_f32_16x16x32_bf16 v[0:3], v[146:149], v[88:91], v[0:3]
	ds_read_b128 v[130:133], v128 offset:23040
	ds_read_b128 v[146:149], v128 offset:32256
	s_nop 3
	v_cvt_pk_bf16_f32 v48, v48, s0
	v_cvt_pk_bf16_f32 v50, v50, s0
	s_waitcnt lgkmcnt(1)
	v_mfma_f32_16x16x32_bf16 v[60:63], v[130:133], v[64:67], v[60:63]
	s_waitcnt lgkmcnt(0)
	v_mfma_f32_16x16x32_bf16 v[8:11], v[146:149], v[64:67], v[8:11]
	ds_read_b128 v[130:133], v128 offset:23104
	ds_read_b128 v[146:149], v128 offset:32320
	s_waitcnt lgkmcnt(1)
	v_mfma_f32_16x16x32_bf16 v[60:63], v[130:133], v[88:91], v[60:63]
	s_waitcnt lgkmcnt(0)
	v_mfma_f32_16x16x32_bf16 v[8:11], v[146:149], v[88:91], v[8:11]
	ds_read_b128 v[130:133], v128 offset:25344
	ds_read_b128 v[146:149], v128 offset:34560
	s_waitcnt lgkmcnt(1)
	v_mfma_f32_16x16x32_bf16 v[52:55], v[130:133], v[64:67], v[52:55]
	s_waitcnt lgkmcnt(0)
	v_mfma_f32_16x16x32_bf16 v[4:7], v[146:149], v[64:67], v[4:7]
	ds_read_b128 v[64:67], v128 offset:25408
	ds_read_b128 v[128:131], v128 offset:34624
	s_waitcnt lgkmcnt(1)
	v_mfma_f32_16x16x32_bf16 v[52:55], v[64:67], v[88:91], v[52:55]
	global_store_short v93, v56, s[20:21]
	v_cvt_pk_bf16_f32 v64, v57, s0
	global_store_short v112, v64, s[20:21]
	global_store_short v113, v58, s[20:21]
	v_cvt_pk_bf16_f32 v58, v59, s0
	global_store_short v114, v58, s[20:21]
	global_store_short v115, v48, s[20:21]
	v_cvt_pk_bf16_f32 v56, v49, s0
	global_store_short v116, v56, s[20:21]
	global_store_short v117, v50, s[20:21]
	v_cvt_pk_bf16_f32 v50, v51, s0
	global_store_short v118, v50, s[20:21]
	v_cvt_pk_bf16_f32 v50, v60, s0
	global_store_short v119, v50, s[20:21]
	v_cvt_pk_bf16_f32 v50, v61, s0
	global_store_short v120, v50, s[20:21]
	v_cvt_pk_bf16_f32 v50, v62, s0
	global_store_short v121, v50, s[20:21]
	v_cvt_pk_bf16_f32 v50, v63, s0
	global_store_short v122, v50, s[20:21]
	v_cvt_pk_bf16_f32 v50, v52, s0
	global_store_short v123, v50, s[20:21]
	v_cvt_pk_bf16_f32 v50, v53, s0
	global_store_short v124, v50, s[20:21]
	v_cvt_pk_bf16_f32 v50, v54, s0
	s_waitcnt lgkmcnt(0)
	v_mfma_f32_16x16x32_bf16 v[4:7], v[128:131], v[88:91], v[4:7]
	global_store_short v125, v50, s[20:21]
	v_cvt_pk_bf16_f32 v50, v55, s0
	global_store_short v126, v50, s[20:21]
	s_andn2_b64 vcc, exec, s[4:5]
	s_cbranch_vccnz .LBB0_329
	s_bitcmp1_b32 s16, 0
	s_cselect_b32 s4, 0x9000, 0
	v_add3_u32 v48, s4, v108, v109
	v_add3_u32 v49, s4, v111, v109
	s_waitcnt vmcnt(28)
	ds_write_b128 v48, v[16:19]
	s_waitcnt vmcnt(27)
	ds_write_b128 v49, v[20:23]
	s_waitcnt vmcnt(26)
	ds_write_b128 v48, v[24:27] offset:9216
	s_waitcnt vmcnt(25)
	ds_write_b128 v49, v[28:31] offset:9216
	s_waitcnt vmcnt(24)
	ds_write_b128 v48, v[32:35] offset:18432
	s_waitcnt vmcnt(23)
	ds_write_b128 v49, v[36:39] offset:18432
	s_waitcnt vmcnt(22)
	ds_write_b128 v48, v[40:43] offset:27648
	s_waitcnt vmcnt(21)
	ds_write_b128 v49, v[44:47] offset:27648
	s_branch .LBB0_329
